# attention loop 1 row-sum: two interleaved f32 add chains (dependency distance 2) instead of one serial chain
# speedup vs baseline: 1.0027x; 1.0027x over previous
.LBB0_1358:
	s_and_b32 s2, s29, 3
	s_mulk_i32 s2, 0x3000
	v_add_u32_e32 v84, s2, v180
	ds_read_b128 v[80:83], v84
	ds_read_b128 v[184:187], v84 offset:512
	ds_read_b128 v[204:207], v84 offset:2048
	ds_read_b128 v[208:211], v84 offset:2560
	ds_read_b128 v[218:221], v84 offset:4096
	ds_read_b128 v[222:225], v84 offset:4608
	ds_read_b128 v[226:229], v84 offset:6144
	ds_read_b128 v[230:233], v84 offset:6656
	s_and_b32 s2, s75, 0x6000
	v_add_f32_e32 v84, v64, v66
	v_add_u32_e32 v183, s2, v199
	ds_read_b64_tr_b16 v[176:177], v183 offset:49152
	ds_read_b64_tr_b16 v[178:179], v183 offset:49664
	s_waitcnt lgkmcnt(9)
	v_mfma_f32_32x32x16_bf16 v[96:111], v[80:83], v[168:171], v[32:47]
	v_add_f32_e32 v85, v65, v67
	v_add_f32_e32 v84, v68, v84
	v_add_f32_e32 v85, v69, v85
	v_cvt_pk_bf16_f32 v148, v64, v65
	v_cvt_pk_bf16_f32 v149, v66, v67
	ds_read_b64_tr_b16 v[172:173], v183 offset:53248
	ds_read_b64_tr_b16 v[174:175], v183 offset:53760
	v_add_f32_e32 v64, v70, v84
	v_add_f32_e32 v65, v71, v85
	s_waitcnt lgkmcnt(10)
	v_mfma_f32_32x32x16_bf16 v[80:95], v[184:187], v[168:171], v[32:47]
	v_add_f32_e32 v140, v72, v64
	v_add_f32_e32 v141, v73, v65
	v_cvt_pk_bf16_f32 v150, v68, v69
	v_cvt_pk_bf16_f32 v151, v70, v71
	ds_read_b64_tr_b16 v[64:65], v183 offset:50176
	ds_read_b64_tr_b16 v[66:67], v183 offset:50688
	s_waitcnt lgkmcnt(11)
	v_mfma_f32_32x32x16_bf16 v[96:111], v[204:207], v[164:167], v[96:111]
	v_add_f32_e32 v68, v74, v140
	v_add_f32_e32 v69, v75, v141
	v_add_f32_e32 v140, v76, v68
	v_add_f32_e32 v141, v77, v69
	v_cvt_pk_bf16_f32 v152, v72, v73
	v_cvt_pk_bf16_f32 v153, v74, v75
	ds_read_b64_tr_b16 v[68:69], v183 offset:54272
	ds_read_b64_tr_b16 v[70:71], v183 offset:54784
	s_waitcnt lgkmcnt(12)
	v_mfma_f32_32x32x16_bf16 v[80:95], v[208:211], v[164:167], v[80:95]
	v_add_f32_e32 v72, v78, v140
	v_add_f32_e32 v73, v79, v141
	v_add_f32_e32 v140, v48, v72
	v_add_f32_e32 v141, v49, v73
	v_cvt_pk_bf16_f32 v154, v76, v77
	v_cvt_pk_bf16_f32 v155, v78, v79
	ds_read_b64_tr_b16 v[72:73], v183 offset:51200
	ds_read_b64_tr_b16 v[74:75], v183 offset:51712
	s_waitcnt lgkmcnt(13)
	v_mfma_f32_32x32x16_bf16 v[96:111], v[218:221], v[160:163], v[96:111]
	v_add_f32_e32 v76, v50, v140
	v_add_f32_e32 v77, v51, v141
	v_add_f32_e32 v76, v52, v76
	v_add_f32_e32 v77, v53, v77
	v_cvt_pk_bf16_f32 v144, v48, v49
	v_cvt_pk_bf16_f32 v145, v50, v51
	ds_read_b64_tr_b16 v[48:49], v183 offset:55296
	ds_read_b64_tr_b16 v[50:51], v183 offset:55808
	s_waitcnt lgkmcnt(14)
	v_mfma_f32_32x32x16_bf16 v[80:95], v[222:225], v[160:163], v[80:95]
	v_add_f32_e32 v76, v54, v76
	v_add_f32_e32 v77, v55, v77
	v_add_f32_e32 v76, v56, v76
	v_add_f32_e32 v77, v57, v77
	v_cvt_pk_bf16_f32 v146, v52, v53
	v_cvt_pk_bf16_f32 v147, v54, v55
	ds_read_b64_tr_b16 v[52:53], v183 offset:52224
	ds_read_b64_tr_b16 v[54:55], v183 offset:52736
	s_waitcnt lgkmcnt(14)
	v_mfma_f32_32x32x16_bf16 v[96:111], v[226:229], v[156:159], v[96:111]
	v_add_f32_e32 v76, v58, v76
	v_add_f32_e32 v77, v59, v77
	v_add_f32_e32 v76, v60, v76
	v_add_f32_e32 v77, v61, v77
	v_cvt_pk_bf16_f32 v140, v56, v57
	v_cvt_pk_bf16_f32 v141, v58, v59
	ds_read_b64_tr_b16 v[56:57], v183 offset:56320
	ds_read_b64_tr_b16 v[58:59], v183 offset:56832
	v_mfma_f32_32x32x16_bf16 v[80:95], v[230:233], v[156:159], v[80:95]
	v_add_f32_e32 v76, v62, v76
	v_add_f32_e32 v77, v63, v77
	v_add_f32_e32 v76, v76, v77
	v_cvt_pk_bf16_f32 v142, v60, v61
	v_cvt_pk_bf16_f32 v143, v62, v63
	s_cmp_gt_u32 s29, 7
	s_cselect_b64 s[2:3], -1, 0
	s_add_i32 s54, s73, s28
	s_and_b64 s[2:3], s[48:49], s[2:3]
	s_add_i32 s50, s54, -13
	s_cmp_lt_u32 s50, -3
	s_cselect_b64 s[50:51], -1, 0
	s_and_b64 s[2:3], s[2:3], s[50:51]
	s_andn2_b64 vcc, exec, s[2:3]
	s_cbranch_vccnz .LBB0_1360
	v_cmp_lt_u32_e32 vcc, s78, v182
	v_add_u32_e32 v60, 32, v182
	s_nop 0
	v_cndmask_b32_e32 v96, v253, v96, vcc
	v_cmp_lt_u32_e32 vcc, s78, v60
	v_add_u32_e32 v60, 1, v182
	s_nop 0
	v_cndmask_b32_e32 v80, v253, v80, vcc
	v_cmp_lt_u32_e32 vcc, s78, v60
	v_add_u32_e32 v60, 33, v182
	s_nop 0
	v_cndmask_b32_e32 v97, v253, v97, vcc
	v_cmp_lt_u32_e32 vcc, s78, v60
	v_add_u32_e32 v60, 2, v182
	s_nop 0
	v_cndmask_b32_e32 v81, v253, v81, vcc
	v_cmp_lt_u32_e32 vcc, s78, v60
	v_add_u32_e32 v60, 34, v182
	s_nop 0
	v_cndmask_b32_e32 v98, v253, v98, vcc
	v_cmp_lt_u32_e32 vcc, s78, v60
	v_add_u32_e32 v60, 3, v182
	s_nop 0
	v_cndmask_b32_e32 v82, v253, v82, vcc
	v_cmp_lt_u32_e32 vcc, s78, v60
	v_add_u32_e32 v60, 35, v182
	s_nop 0
	v_cndmask_b32_e32 v99, v253, v99, vcc
	v_cmp_lt_u32_e32 vcc, s78, v60
	v_add_u32_e32 v60, 8, v182
	s_nop 0
	v_cndmask_b32_e32 v83, v253, v83, vcc
	v_cmp_lt_u32_e32 vcc, s78, v60
	v_add_u32_e32 v60, 40, v182
	s_nop 0
	v_cndmask_b32_e32 v100, v253, v100, vcc
	v_cmp_lt_u32_e32 vcc, s78, v60
	v_add_u32_e32 v60, 9, v182
	s_nop 0
	v_cndmask_b32_e32 v84, v253, v84, vcc
	v_cmp_lt_u32_e32 vcc, s78, v60
	v_add_u32_e32 v60, 41, v182
	s_nop 0
	v_cndmask_b32_e32 v101, v253, v101, vcc
	v_cmp_lt_u32_e32 vcc, s78, v60
	v_add_u32_e32 v60, 10, v182
	s_nop 0
	v_cndmask_b32_e32 v85, v253, v85, vcc
	v_cmp_lt_u32_e32 vcc, s78, v60
	v_add_u32_e32 v60, 42, v182
	s_nop 0
	v_cndmask_b32_e32 v102, v253, v102, vcc
	v_cmp_lt_u32_e32 vcc, s78, v60
	v_add_u32_e32 v60, 11, v182
	s_nop 0
	v_cndmask_b32_e32 v86, v253, v86, vcc
	v_cmp_lt_u32_e32 vcc, s78, v60
	v_add_u32_e32 v60, 43, v182
	s_nop 0
	v_cndmask_b32_e32 v103, v253, v103, vcc
	v_cmp_lt_u32_e32 vcc, s78, v60
	v_add_u32_e32 v60, 16, v182
	s_nop 0
	v_cndmask_b32_e32 v87, v253, v87, vcc
	v_cmp_lt_u32_e32 vcc, s78, v60
	v_add_u32_e32 v60, 48, v182
	s_nop 0
	v_cndmask_b32_e32 v104, v253, v104, vcc
	v_cmp_lt_u32_e32 vcc, s78, v60
	v_add_u32_e32 v60, 17, v182
	s_nop 0
	v_cndmask_b32_e32 v88, v253, v88, vcc
	v_cmp_lt_u32_e32 vcc, s78, v60
	v_add_u32_e32 v60, 49, v182
	s_nop 0
	v_cndmask_b32_e32 v105, v253, v105, vcc
	v_cmp_lt_u32_e32 vcc, s78, v60
	v_add_u32_e32 v60, 18, v182
	s_nop 0
	v_cndmask_b32_e32 v89, v253, v89, vcc
	v_cmp_lt_u32_e32 vcc, s78, v60
	v_add_u32_e32 v60, 50, v182
	s_nop 0
	v_cndmask_b32_e32 v106, v253, v106, vcc
	v_cmp_lt_u32_e32 vcc, s78, v60
	v_add_u32_e32 v60, 19, v182
	s_nop 0
	v_cndmask_b32_e32 v90, v253, v90, vcc
	v_cmp_lt_u32_e32 vcc, s78, v60
	v_add_u32_e32 v60, 51, v182
	s_nop 0
	v_cndmask_b32_e32 v107, v253, v107, vcc
	v_cmp_lt_u32_e32 vcc, s78, v60
	v_add_u32_e32 v60, 24, v182
	s_nop 0
	v_cndmask_b32_e32 v91, v253, v91, vcc
	v_cmp_lt_u32_e32 vcc, s78, v60
	v_add_u32_e32 v60, 56, v182
	s_nop 0
	v_cndmask_b32_e32 v108, v253, v108, vcc
	v_cmp_lt_u32_e32 vcc, s78, v60
	v_add_u32_e32 v60, 25, v182
	s_nop 0
	v_cndmask_b32_e32 v92, v253, v92, vcc
	v_cmp_lt_u32_e32 vcc, s78, v60
	v_add_u32_e32 v60, 57, v182
	s_nop 0
	v_cndmask_b32_e32 v109, v253, v109, vcc
	v_cmp_lt_u32_e32 vcc, s78, v60
	v_add_u32_e32 v60, 26, v182
	s_nop 0
	v_cndmask_b32_e32 v93, v253, v93, vcc
	v_cmp_lt_u32_e32 vcc, s78, v60
	v_add_u32_e32 v60, 58, v182
	s_nop 0
	v_cndmask_b32_e32 v110, v253, v110, vcc
	v_cmp_lt_u32_e32 vcc, s78, v60
	v_add_u32_e32 v60, 27, v182
	s_nop 0
	v_cndmask_b32_e32 v94, v253, v94, vcc
	v_cmp_lt_u32_e32 vcc, s78, v60
	v_add_u32_e32 v60, 59, v182
	s_nop 0
	v_cndmask_b32_e32 v111, v253, v111, vcc
	v_cmp_lt_u32_e32 vcc, s78, v60
	s_nop 1
	v_cndmask_b32_e32 v95, v253, v95, vcc

.LBB0_1374:
	s_add_i32 s2, s28, -2
	s_and_b32 s2, s2, 3
	s_mulk_i32 s2, 0x3000
	v_add_u32_e32 v52, s2, v180
	ds_read_b128 v[48:51], v52
	ds_read_b128 v[184:187], v52 offset:512
	ds_read_b128 v[204:207], v52 offset:2048
	ds_read_b128 v[208:211], v52 offset:2560
	ds_read_b128 v[218:221], v52 offset:4096
	ds_read_b128 v[222:225], v52 offset:4608
	ds_read_b128 v[226:229], v52 offset:6144
	ds_read_b128 v[230:233], v52 offset:6656
	s_add_i32 s2, s75, 0xffffa000
	s_and_b32 s2, s2, 0x6000
	v_add_f32_e32 v52, v96, v98
	v_add_u32_e32 v203, s2, v199
	ds_read_b64_tr_b16 v[176:177], v203 offset:49152
	ds_read_b64_tr_b16 v[178:179], v203 offset:49664
	s_waitcnt lgkmcnt(9)
	v_mfma_f32_32x32x16_bf16 v[64:79], v[48:51], v[168:171], v[32:47]
	v_add_f32_e32 v53, v97, v99
	v_add_f32_e32 v52, v100, v52
	v_add_f32_e32 v53, v101, v53
	v_cvt_pk_bf16_f32 v148, v96, v97
	v_cvt_pk_bf16_f32 v149, v98, v99
	ds_read_b64_tr_b16 v[172:173], v203 offset:53248
	ds_read_b64_tr_b16 v[174:175], v203 offset:53760
	v_add_f32_e32 v48, v102, v52
	v_add_f32_e32 v49, v103, v53
	v_add_f32_e32 v140, v104, v48
	v_add_f32_e32 v141, v105, v49
	s_waitcnt lgkmcnt(10)
	v_mfma_f32_32x32x16_bf16 v[48:63], v[184:187], v[168:171], v[32:47]
	v_cvt_pk_bf16_f32 v150, v100, v101
	v_cvt_pk_bf16_f32 v151, v102, v103
	ds_read_b64_tr_b16 v[96:97], v203 offset:50176
	ds_read_b64_tr_b16 v[98:99], v203 offset:50688
	s_waitcnt lgkmcnt(11)
	v_mfma_f32_32x32x16_bf16 v[64:79], v[204:207], v[164:167], v[64:79]
	v_add_f32_e32 v100, v106, v140
	v_add_f32_e32 v101, v107, v141
	v_add_f32_e32 v140, v108, v100
	v_add_f32_e32 v141, v109, v101
	v_cvt_pk_bf16_f32 v152, v104, v105
	v_cvt_pk_bf16_f32 v153, v106, v107
	ds_read_b64_tr_b16 v[100:101], v203 offset:54272
	ds_read_b64_tr_b16 v[102:103], v203 offset:54784
	s_waitcnt lgkmcnt(12)
	v_mfma_f32_32x32x16_bf16 v[48:63], v[208:211], v[164:167], v[48:63]
	v_add_f32_e32 v104, v110, v140
	v_add_f32_e32 v105, v111, v141
	v_add_f32_e32 v140, v80, v104
	v_add_f32_e32 v141, v81, v105
	v_cvt_pk_bf16_f32 v154, v108, v109
	v_cvt_pk_bf16_f32 v155, v110, v111
	ds_read_b64_tr_b16 v[104:105], v203 offset:51200
	ds_read_b64_tr_b16 v[106:107], v203 offset:51712
	s_waitcnt lgkmcnt(13)
	v_mfma_f32_32x32x16_bf16 v[64:79], v[218:221], v[160:163], v[64:79]
	v_add_f32_e32 v108, v82, v140
	v_add_f32_e32 v109, v83, v141
	v_add_f32_e32 v108, v84, v108
	v_add_f32_e32 v109, v85, v109
	v_cvt_pk_bf16_f32 v144, v80, v81
	v_cvt_pk_bf16_f32 v145, v82, v83
	ds_read_b64_tr_b16 v[80:81], v203 offset:55296
	ds_read_b64_tr_b16 v[82:83], v203 offset:55808
	s_waitcnt lgkmcnt(14)
	v_mfma_f32_32x32x16_bf16 v[48:63], v[222:225], v[160:163], v[48:63]
	v_add_f32_e32 v108, v86, v108
	v_add_f32_e32 v109, v87, v109
	v_add_f32_e32 v108, v88, v108
	v_add_f32_e32 v109, v89, v109
	v_cvt_pk_bf16_f32 v146, v84, v85
	v_cvt_pk_bf16_f32 v147, v86, v87
	ds_read_b64_tr_b16 v[84:85], v203 offset:52224
	ds_read_b64_tr_b16 v[86:87], v203 offset:52736
	s_waitcnt lgkmcnt(14)
	v_mfma_f32_32x32x16_bf16 v[64:79], v[226:229], v[156:159], v[64:79]
	v_add_f32_e32 v108, v90, v108
	v_add_f32_e32 v109, v91, v109
	v_add_f32_e32 v108, v92, v108
	v_add_f32_e32 v109, v93, v109
	v_cvt_pk_bf16_f32 v140, v88, v89
	v_cvt_pk_bf16_f32 v141, v90, v91
	ds_read_b64_tr_b16 v[88:89], v203 offset:56320
	ds_read_b64_tr_b16 v[90:91], v203 offset:56832
	v_mfma_f32_32x32x16_bf16 v[48:63], v[230:233], v[156:159], v[48:63]
	v_add_f32_e32 v108, v94, v108
	v_add_f32_e32 v109, v95, v109
	v_add_f32_e32 v108, v108, v109
	v_cvt_pk_bf16_f32 v142, v92, v93
	v_cvt_pk_bf16_f32 v143, v94, v95
	s_cmp_gt_u32 s29, 6
	s_cselect_b64 s[2:3], -1, 0
	s_and_b64 s[2:3], s[48:49], s[2:3]
	s_add_i32 s54, s54, -12
	s_cmp_lt_u32 s54, -3
	s_cselect_b64 s[50:51], -1, 0
	s_and_b64 s[2:3], s[2:3], s[50:51]
	s_andn2_b64 vcc, exec, s[2:3]
	s_cbranch_vccnz .LBB0_1376
	v_add_u32_e32 v92, 64, v182
	v_cmp_lt_u32_e32 vcc, s78, v92
	v_add_u32_e32 v92, 0x60, v182
	s_nop 0
	v_cndmask_b32_e32 v64, v253, v64, vcc
	v_cmp_lt_u32_e32 vcc, s78, v92
	v_add_u32_e32 v92, 0x41, v182
	s_nop 0
	v_cndmask_b32_e32 v48, v253, v48, vcc
	v_cmp_lt_u32_e32 vcc, s78, v92
	v_add_u32_e32 v92, 0x61, v182
	s_nop 0
	v_cndmask_b32_e32 v65, v253, v65, vcc
	v_cmp_lt_u32_e32 vcc, s78, v92
	v_add_u32_e32 v92, 0x42, v182
	s_nop 0
	v_cndmask_b32_e32 v49, v253, v49, vcc
	v_cmp_lt_u32_e32 vcc, s78, v92
	v_add_u32_e32 v92, 0x62, v182
	s_nop 0
	v_cndmask_b32_e32 v66, v253, v66, vcc
	v_cmp_lt_u32_e32 vcc, s78, v92
	v_add_u32_e32 v92, 0x43, v182
	s_nop 0
	v_cndmask_b32_e32 v50, v253, v50, vcc
	v_cmp_lt_u32_e32 vcc, s78, v92
	v_add_u32_e32 v92, 0x63, v182
	s_nop 0
	v_cndmask_b32_e32 v67, v253, v67, vcc
	v_cmp_lt_u32_e32 vcc, s78, v92
	v_add_u32_e32 v92, 0x48, v182
	s_nop 0
	v_cndmask_b32_e32 v51, v253, v51, vcc
	v_cmp_lt_u32_e32 vcc, s78, v92
	v_add_u32_e32 v92, 0x68, v182
	s_nop 0
	v_cndmask_b32_e32 v68, v253, v68, vcc
	v_cmp_lt_u32_e32 vcc, s78, v92
	v_add_u32_e32 v92, 0x49, v182
	s_nop 0
	v_cndmask_b32_e32 v52, v253, v52, vcc
	v_cmp_lt_u32_e32 vcc, s78, v92
	v_add_u32_e32 v92, 0x69, v182
	s_nop 0
	v_cndmask_b32_e32 v69, v253, v69, vcc
	v_cmp_lt_u32_e32 vcc, s78, v92
	v_add_u32_e32 v92, 0x4a, v182
	s_nop 0
	v_cndmask_b32_e32 v53, v253, v53, vcc
	v_cmp_lt_u32_e32 vcc, s78, v92
	v_add_u32_e32 v92, 0x6a, v182
	s_nop 0
	v_cndmask_b32_e32 v70, v253, v70, vcc
	v_cmp_lt_u32_e32 vcc, s78, v92
	v_add_u32_e32 v92, 0x4b, v182
	s_nop 0
	v_cndmask_b32_e32 v54, v253, v54, vcc
	v_cmp_lt_u32_e32 vcc, s78, v92
	v_add_u32_e32 v92, 0x6b, v182
	s_nop 0
	v_cndmask_b32_e32 v71, v253, v71, vcc
	v_cmp_lt_u32_e32 vcc, s78, v92
	v_add_u32_e32 v92, 0x50, v182
	s_nop 0
	v_cndmask_b32_e32 v55, v253, v55, vcc
	v_cmp_lt_u32_e32 vcc, s78, v92
	v_add_u32_e32 v92, 0x70, v182
	s_nop 0
	v_cndmask_b32_e32 v72, v253, v72, vcc
	v_cmp_lt_u32_e32 vcc, s78, v92
	v_add_u32_e32 v92, 0x51, v182
	s_nop 0
	v_cndmask_b32_e32 v56, v253, v56, vcc
	v_cmp_lt_u32_e32 vcc, s78, v92
	v_add_u32_e32 v92, 0x71, v182
	s_nop 0
	v_cndmask_b32_e32 v73, v253, v73, vcc
	v_cmp_lt_u32_e32 vcc, s78, v92
	v_add_u32_e32 v92, 0x52, v182
	s_nop 0
	v_cndmask_b32_e32 v57, v253, v57, vcc
	v_cmp_lt_u32_e32 vcc, s78, v92
	v_add_u32_e32 v92, 0x72, v182
	s_nop 0
	v_cndmask_b32_e32 v74, v253, v74, vcc
	v_cmp_lt_u32_e32 vcc, s78, v92
	v_add_u32_e32 v92, 0x53, v182
	s_nop 0
	v_cndmask_b32_e32 v58, v253, v58, vcc
	v_cmp_lt_u32_e32 vcc, s78, v92
	v_add_u32_e32 v92, 0x73, v182
	s_nop 0
	v_cndmask_b32_e32 v75, v253, v75, vcc
	v_cmp_lt_u32_e32 vcc, s78, v92
	v_add_u32_e32 v92, 0x58, v182
	s_nop 0
	v_cndmask_b32_e32 v59, v253, v59, vcc
	v_cmp_lt_u32_e32 vcc, s78, v92
	v_add_u32_e32 v92, 0x78, v182
	s_nop 0
	v_cndmask_b32_e32 v76, v253, v76, vcc
	v_cmp_lt_u32_e32 vcc, s78, v92
	v_add_u32_e32 v92, 0x59, v182
	s_nop 0
	v_cndmask_b32_e32 v60, v253, v60, vcc
	v_cmp_lt_u32_e32 vcc, s78, v92
	v_add_u32_e32 v92, 0x79, v182
	s_nop 0
	v_cndmask_b32_e32 v77, v253, v77, vcc
	v_cmp_lt_u32_e32 vcc, s78, v92
	v_add_u32_e32 v92, 0x5a, v182
	s_nop 0
	v_cndmask_b32_e32 v61, v253, v61, vcc
	v_cmp_lt_u32_e32 vcc, s78, v92
	v_add_u32_e32 v92, 0x7a, v182
	s_nop 0
	v_cndmask_b32_e32 v78, v253, v78, vcc
	v_cmp_lt_u32_e32 vcc, s78, v92
	v_add_u32_e32 v92, 0x5b, v182
	s_nop 0
	v_cndmask_b32_e32 v62, v253, v62, vcc
	v_cmp_lt_u32_e32 vcc, s78, v92
	v_add_u32_e32 v92, 0x7b, v182
	s_nop 0
	v_cndmask_b32_e32 v79, v253, v79, vcc
	v_cmp_lt_u32_e32 vcc, s78, v92
	s_nop 1
	v_cndmask_b32_e32 v63, v253, v63, vcc
